# latent sigmoid gates stored/reloaded in MFMA-fragment order (workgroup-private buffer): full 128-byte-line stores and loads instead of 64-byte row pieces
# speedup vs baseline: 1.0381x; 1.0044x over previous
; __device__ __forceinline__ unsigned pk2(float lo, float hi) { unsigned r; asm volatile("v_cvt_pk_bf16_f32 %0, %1, %2" : "=v"(r) : "v"(lo), "v"(hi)); return r; }
; __device__ __forceinline__ float fast_sigmoid(float x) { return __builtin_amdgcn_rcpf(1.0f + __builtin_amdgcn_exp2f(-x * LOG2E)); }
; #define GAS __attribute__((address_space(1)))
; template <class T> __device__ __forceinline__ GAS T* gptr(T* q) { return (GAS T*)(unsigned long long)uptr(q); }
; __device__ __forceinline__ void gemm_epilogue(LAS unsigned char* lds, const GD& gd, const f32x4 (&acc)[2][2][4][2], const Unit& u) {
;     ...
;     int ldc = __builtin_amdgcn_readfirstlane(gd.ldc);
;     const int lcol = wc * 32 + 8 * fq;
;     const bool ctx_gate_out = (mode == M_P1) && (u.pn >= 5);
;     const bool ctx_gate_in = (row_u >= NL) && (gd.auxc != nullptr);
;     const int emode = ctx_gate_out ? (int)M_GATE : mode;
;     if (ctx_gate_out) ldc = 3072;
;     const int apitch = ctx_gate_in ? 3072 : 1024;
;     GAS bf16_t* outu = gptr(ctx_gate_out ? gd.auxc + (size_t)(row_u - NL) * 3072 + (u.pn - 5) * BM : gd.out + (size_t)row_u * ldc + u.pn * BM);
;     GAS const bf16_t* auxu = gptr(ctx_gate_in ? (const bf16_t*)gd.auxc + (size_t)(row_u - NL) * 3072 + u.pn * BM : gd.aux + (size_t)row_u * 1024 + u.pn * BM);
;     const unsigned ooff = (unsigned)(lrow * ldc + lcol), goff = (unsigned)(lrow * apitch + lcol);
;     ...
;             if (emode == M_GATE) {
; #pragma unroll
;                 for (int j = 0; j < 4; ++j) { v0[j] = fast_sigmoid(v0[j]); v1[j] = fast_sigmoid(v1[j]); }
;             }
;             u32x4 w; w.x = pk2(v0[0], v0[1]); w.y = pk2(v0[2], v0[3]); w.z = pk2(v1[0], v1[1]); w.w = pk2(v1[2], v1[3]);
;             *(GAS u32x4*)(outu + ooff + (ai * HALF + m * 16) * ldc + bj * HALF) = w;
.LBB0_473:
	s_and_b64 s[48:49], s[44:45], exec
	s_cselect_b32 s90, 0xc00, s2
	s_ashr_i32 s7, s6, 31
	v_lshlrev_b32_e32 v96, 3, v251
	s_lshl_b64 s[6:7], s[6:7], 1
	v_lshl_or_b32 v96, s15, 5, v96
	s_add_u32 s96, s46, s6
	s_addc_u32 s97, s47, s7
	v_mad_u64_u32 v[156:157], s[6:7], s90, v174, v[96:97]
	s_cmp_lg_u32 s78, 2
	s_cbranch_scc1 .Lmy_nogf1
	v_mov_b32_e32 v132, 0x240a8
	ds_read_b64 v[132:133], v132
	s_and_b32 s46, s15, 1
	s_lshl_b32 s46, s46, 12
	s_lshr_b32 s47, s15, 1
	s_lshl_b32 s48, s98, 1
	s_add_u32 s47, s47, s48
	s_lshl_b32 s47, s47, 14
	s_add_u32 s46, s46, s47
	v_lshlrev_b32_e32 v156, 8, v251
	v_lshl_add_u32 v156, v252, 3, v156
	v_add_u32_e32 v156, s46, v156
	v_mov_b32_e32 v157, 0
	s_movk_i32 s90, 64
	s_lshl_b32 s46, s33, 19
	s_lshl_b32 s47, s80, 17
	s_add_u32 s46, s46, s47
	s_add_u32 s46, s46, 0x6300000
	s_waitcnt lgkmcnt(0)
	v_readfirstlane_b32 s92, v132
	v_readfirstlane_b32 s93, v133
	s_nop 3
	s_add_u32 s92, s92, s46
	s_addc_u32 s93, s93, 0
.Lmy_nogf1:
	s_add_i32 s2, s78, -3
	s_cmp_gt_u32 s2, 1
	s_mov_b64 s[6:7], -1
	s_cbranch_scc0 .LBB0_555
	s_cmp_lt_i32 s33, 64
	s_cselect_b64 s[6:7], -1, 0
	s_and_b64 s[4:5], s[4:5], s[6:7]
	s_cmp_lt_i32 s80, 3
	s_cselect_b64 s[6:7], -1, 0
	v_lshrrev_b32_e32 v132, 4, v211
	s_and_b64 s[50:51], s[4:5], s[6:7]
	s_bitcmp0_b32 s11, 6
	v_lshlrev_b32_e32 v132, 6, v132
	s_cselect_b64 s[48:49], -1, 0
	v_and_b32_e32 v132, 64, v132
	s_add_i32 s2, 0, 0x22000
	v_add_u32_e32 v159, s88, v174
	v_add_u32_e32 v164, s2, v132
	v_cndmask_b32_e64 v132, 0, 1, s[50:51]
	v_cmp_ne_u32_e64 s[46:47], 1, v132
	s_andn2_b64 vcc, exec, s[50:51]
	v_lshrrev_b32_e32 v165, 6, v159
	s_cbranch_vccnz .LBB0_476
	v_cndmask_b32_e64 v132, v252, v165, s[48:49]
	v_lshlrev_b32_e32 v132, 7, v132
	v_and_b32_e32 v132, 0x1f80, v132
	v_add_u32_e32 v132, v164, v132
	ds_read_b128 v[140:143], v132
	ds_read_b128 v[136:139], v132 offset:16
	ds_read_b128 v[144:147], v132 offset:32
	ds_read_b128 v[132:135], v132 offset:48

; #define GAS __attribute__((address_space(1)))
; __device__ __forceinline__ void gemm_epilogue(LAS unsigned char* lds, const GD& gd, const f32x4 (&acc)[2][2][4][2], const Unit& u) {
;     ...
;     if (mode == M_YSET || mode == M_YADD) {
; #pragma unroll
;         for (int am = 0; am < 8 / MBG; ++am) {
;             const int ai = (am * MBG) >> 2, m0 = (am * MBG) & 3;
;             u32x4 gw[MBG][2], yw[MBG][2];
; #pragma unroll
;             for (int mm = 0; mm < MBG; ++mm)
; #pragma unroll
;                 for (int bj = 0; bj < 2; ++bj) {
;                     const int ro = ai * HALF + (m0 + mm) * 16;
;                     gw[mm][bj] = *(GAS const u32x4*)(auxu + goff + ro * apitch + bj * HALF);
;                     if (mode == M_YADD) yw[mm][bj] = *(GAS const u32x4*)(outu + ooff + ro * ldc + bj * HALF);
;                 }
;             asm volatile("" ::: "memory");
.LBB0_555:
	s_and_b64 vcc, exec, s[6:7]
	s_cbranch_vccz .LBB0_621
	s_cmp_eq_u32 s78, 4
	s_cselect_b64 s[4:5], -1, 0
	s_and_b64 s[6:7], s[94:95], exec
	s_movk_i32 s2, 0xc00
	s_cselect_b32 s6, s2, 0x400
	v_mul_lo_u32 v132, v174, s6
	v_or_b32_e32 v96, v132, v96
	s_and_b64 s[46:47], s[94:95], exec
	s_cbranch_scc1 .Lmy_nogf2
	v_mov_b32_e32 v132, 0x240a8
	ds_read_b64 v[132:133], v132
	s_and_b32 s46, s15, 1
	s_lshl_b32 s46, s46, 12
	s_lshr_b32 s47, s15, 1
	s_lshl_b32 s48, s98, 1
	s_add_u32 s47, s47, s48
	s_lshl_b32 s47, s47, 14
	s_add_u32 s46, s46, s47
	v_lshlrev_b32_e32 v96, 8, v251
	v_lshl_add_u32 v96, v252, 3, v96
	v_add_u32_e32 v96, s46, v96
	s_movk_i32 s6, 64
	s_lshl_b32 s46, s33, 19
	s_lshl_b32 s47, s80, 17
	s_add_u32 s46, s46, s47
	s_add_u32 s46, s46, 0x6300000
	s_waitcnt lgkmcnt(0)
	v_readfirstlane_b32 s96, v132
	v_readfirstlane_b32 s97, v133
	s_nop 3
	s_add_u32 s96, s96, s46
	s_addc_u32 s97, s97, 0
.Lmy_nogf2:
	v_lshl_add_u64 v[164:165], v[96:97], 1, s[96:97]
	global_load_dwordx4 v[160:163], v[164:165], off
	v_mov_b32_e32 v157, v97
	s_cmp_lg_u32 s78, 4
	v_lshl_add_u64 v[168:169], v[156:157], 1, s[92:93]
	s_cbranch_scc1 .LBB0_558
	global_load_dwordx4 v[144:147], v[168:169], off
